# GEMM K-loops: first iteration peeled with SrcC=0 on each accumulator's first MFMA; the 128 per-tile accumulator-zeroing moves removed
# speedup vs baseline: 1.0127x; 1.0026x over previous
.LBB0_62:
	v_and_b32_e32 v1, 15, v0
	v_and_b32_e32 v2, 48, v0
	v_lshlrev_b32_e32 v1, 6, v1
	v_lshlrev_b32_e32 v0, 2, v0
	v_or_b32_e32 v3, v1, v2
	v_and_b32_e32 v0, 32, v0
	s_lshl_b32 s7, s37, 13
	v_bitop3_b32 v148, v3, s7, v0 bitop3:0xde
	s_lshl_b32 s7, s9, 6
	v_bitop3_b32 v1, v1, v0, v2 bitop3:0x36
	s_and_b32 s7, s7, 0x3000
	v_or_b32_e32 v0, s7, v1
	s_add_u32 s7, s94, s14
	s_addc_u32 s20, s95, s15
	s_add_u32 s21, s31, s38
	s_addc_u32 s26, s34, s55
	s_add_u32 s2, s94, s2
	s_addc_u32 s3, s95, s3
	s_add_u32 s18, s31, s18
	s_addc_u32 s19, s34, s19
	v_or_b32_e32 v149, 0x10000, v0
	v_or_b32_e32 v147, 0x14000, v0
	v_or_b32_e32 v145, 0x18000, v0
	v_or_b32_e32 v143, 0x1c000, v0
	s_add_u32 s27, s7, 0x100
	v_add_u32_e32 v146, 0x4000, v148
	v_add_u32_e32 v144, 0x8000, v148
	v_add_u32_e32 v142, 0xc000, v148
	s_addc_u32 s28, s20, 0
	s_mov_b32 s29, -2
	s_mov_b64 s[14:15], 0
	s_nop 0
	ds_read_b128 v[150:153], v149 offset:0
	ds_read_b128 v[158:161], v149 offset:1024
	ds_read_b128 v[162:165], v149 offset:2048
	ds_read_b128 v[166:169], v149 offset:3072
	s_add_u32 s37, s7, s14
	s_addc_u32 s39, s20, s15
	s_add_u32 s38, s37, 0x80
	v_add_u32_e32 v156, 0xc000, v135
	s_addc_u32 s39, s39, 0
	v_readfirstlane_b32 s37, v156
	v_add_u32_e32 v157, 0xe000, v135
	s_mov_b32 m0, s37
	ds_read_b128 v[170:173], v148 offset:0
	ds_read_b128 v[178:181], v148 offset:1024
	ds_read_b128 v[182:185], v148 offset:2048
	ds_read_b128 v[186:189], v148 offset:3072
	ds_read_b128 v[190:193], v148 offset:4096
	ds_read_b128 v[194:197], v148 offset:5120
	ds_read_b128 v[198:201], v148 offset:6144
	ds_read_b128 v[202:205], v148 offset:7168
	global_load_lds_dwordx4 v130, s[38:39]
	s_add_u32 m0, m0, 0x2000
	s_nop 0
	global_load_lds_dwordx4 v128, s[38:39]
	ds_read_b128 v[206:209], v147 offset:0
	ds_read_b128 v[210:213], v147 offset:1024
	ds_read_b128 v[214:217], v147 offset:2048
	ds_read_b128 v[218:221], v147 offset:3072
	s_waitcnt vmcnt(8)
	s_waitcnt lgkmcnt(0)
	s_barrier
	s_waitcnt lgkmcnt(0)
	s_waitcnt lgkmcnt(0)
	s_setprio 1
	v_mfma_f32_16x16x32_bf16 v[124:127], v[150:153], v[170:173], 0
	v_mfma_f32_16x16x32_bf16 v[120:123], v[162:165], v[170:173], 0
	v_mfma_f32_16x16x32_bf16 v[116:119], v[150:153], v[182:185], 0
	v_mfma_f32_16x16x32_bf16 v[112:115], v[162:165], v[182:185], 0
	v_mfma_f32_16x16x32_bf16 v[108:111], v[150:153], v[190:193], 0
	v_mfma_f32_16x16x32_bf16 v[104:107], v[162:165], v[190:193], 0
	v_mfma_f32_16x16x32_bf16 v[100:103], v[150:153], v[198:201], 0
	v_mfma_f32_16x16x32_bf16 v[96:99], v[162:165], v[198:201], 0
	v_mfma_f32_16x16x32_bf16 v[124:127], v[158:161], v[178:181], v[124:127]
	v_mfma_f32_16x16x32_bf16 v[120:123], v[166:169], v[178:181], v[120:123]
	v_mfma_f32_16x16x32_bf16 v[116:119], v[158:161], v[186:189], v[116:119]
	v_mfma_f32_16x16x32_bf16 v[112:115], v[166:169], v[186:189], v[112:115]
	v_mfma_f32_16x16x32_bf16 v[108:111], v[158:161], v[194:197], v[108:111]
	v_mfma_f32_16x16x32_bf16 v[104:107], v[166:169], v[194:197], v[104:107]
	v_mfma_f32_16x16x32_bf16 v[100:103], v[158:161], v[202:205], v[100:103]
	v_mfma_f32_16x16x32_bf16 v[96:99], v[166:169], v[202:205], v[96:99]
	s_setprio 0
	s_waitcnt lgkmcnt(0)
	s_setprio 1
	v_mfma_f32_16x16x32_bf16 v[92:95], v[206:209], v[170:173], 0
	v_mfma_f32_16x16x32_bf16 v[88:91], v[214:217], v[170:173], 0
	v_mfma_f32_16x16x32_bf16 v[84:87], v[206:209], v[182:185], 0
	v_mfma_f32_16x16x32_bf16 v[80:83], v[214:217], v[182:185], 0
	v_mfma_f32_16x16x32_bf16 v[76:79], v[206:209], v[190:193], 0
	v_mfma_f32_16x16x32_bf16 v[72:75], v[214:217], v[190:193], 0
	v_mfma_f32_16x16x32_bf16 v[68:71], v[206:209], v[198:201], 0
	v_mfma_f32_16x16x32_bf16 v[64:67], v[214:217], v[198:201], 0
	v_mfma_f32_16x16x32_bf16 v[92:95], v[210:213], v[178:181], v[92:95]
	v_mfma_f32_16x16x32_bf16 v[88:91], v[218:221], v[178:181], v[88:91]
	v_mfma_f32_16x16x32_bf16 v[84:87], v[210:213], v[186:189], v[84:87]
	v_mfma_f32_16x16x32_bf16 v[80:83], v[218:221], v[186:189], v[80:83]
	v_mfma_f32_16x16x32_bf16 v[76:79], v[210:213], v[194:197], v[76:79]
	v_mfma_f32_16x16x32_bf16 v[72:75], v[218:221], v[194:197], v[72:75]
	v_mfma_f32_16x16x32_bf16 v[68:71], v[210:213], v[202:205], v[68:71]
	v_mfma_f32_16x16x32_bf16 v[64:67], v[218:221], v[202:205], v[64:67]
	s_setprio 0
	s_barrier
	s_add_u32 s37, s21, s14
	s_addc_u32 s40, s26, s15
	s_add_u32 s38, s37, 0x100
	s_addc_u32 s39, s40, 0
	v_readfirstlane_b32 s41, v141
	s_mov_b32 m0, s41
	s_nop 0
	global_load_lds_dwordx4 v176, s[38:39]
	s_add_u32 m0, m0, 0x2000
	s_nop 0
	global_load_lds_dwordx4 v132, s[38:39]
	s_add_u32 s41, s2, s14
	s_addc_u32 s42, s3, s15
	s_add_u32 s38, s41, 0x100
	s_addc_u32 s39, s42, 0
	v_readfirstlane_b32 s43, v135
	s_mov_b32 m0, s43
	ds_read_b128 v[170:173], v146 offset:0
	ds_read_b128 v[178:181], v146 offset:1024
	ds_read_b128 v[182:185], v146 offset:2048
	ds_read_b128 v[186:189], v146 offset:3072
	ds_read_b128 v[190:193], v146 offset:4096
	ds_read_b128 v[194:197], v146 offset:5120
	ds_read_b128 v[198:201], v146 offset:6144
	ds_read_b128 v[202:205], v146 offset:7168
	global_load_lds_dwordx4 v130, s[38:39]
	s_add_u32 m0, m0, 0x2000
	s_nop 0
	global_load_lds_dwordx4 v128, s[38:39]
	s_add_u32 s43, s18, s14
	s_addc_u32 s44, s19, s15
	s_add_u32 s38, s43, 0x100
	s_addc_u32 s39, s44, 0
	v_readfirstlane_b32 s45, v139
	s_mov_b32 m0, s45
	s_nop 0
	global_load_lds_dwordx4 v176, s[38:39]
	s_add_u32 m0, m0, 0x2000
	s_nop 0
	global_load_lds_dwordx4 v132, s[38:39]
	s_waitcnt vmcnt(8)
	s_waitcnt lgkmcnt(0)
	s_barrier
	s_waitcnt lgkmcnt(0)
	s_setprio 1
	v_mfma_f32_16x16x32_bf16 v[60:63], v[150:153], v[170:173], 0
	v_mfma_f32_16x16x32_bf16 v[56:59], v[162:165], v[170:173], 0
	v_mfma_f32_16x16x32_bf16 v[52:55], v[150:153], v[182:185], 0
	v_mfma_f32_16x16x32_bf16 v[48:51], v[162:165], v[182:185], 0
	v_mfma_f32_16x16x32_bf16 v[44:47], v[150:153], v[190:193], 0
	v_mfma_f32_16x16x32_bf16 v[40:43], v[162:165], v[190:193], 0
	v_mfma_f32_16x16x32_bf16 v[36:39], v[150:153], v[198:201], 0
	v_mfma_f32_16x16x32_bf16 v[32:35], v[162:165], v[198:201], 0
	v_mfma_f32_16x16x32_bf16 v[60:63], v[158:161], v[178:181], v[60:63]
	v_mfma_f32_16x16x32_bf16 v[56:59], v[166:169], v[178:181], v[56:59]
	v_mfma_f32_16x16x32_bf16 v[52:55], v[158:161], v[186:189], v[52:55]
	v_mfma_f32_16x16x32_bf16 v[48:51], v[166:169], v[186:189], v[48:51]
	v_mfma_f32_16x16x32_bf16 v[44:47], v[158:161], v[194:197], v[44:47]
	v_mfma_f32_16x16x32_bf16 v[40:43], v[166:169], v[194:197], v[40:43]
	v_mfma_f32_16x16x32_bf16 v[36:39], v[158:161], v[202:205], v[36:39]
	v_mfma_f32_16x16x32_bf16 v[32:35], v[166:169], v[202:205], v[32:35]
	s_setprio 0
	s_setprio 1
	v_mfma_f32_16x16x32_bf16 v[28:31], v[206:209], v[170:173], 0
	v_mfma_f32_16x16x32_bf16 v[24:27], v[214:217], v[170:173], 0
	v_mfma_f32_16x16x32_bf16 v[20:23], v[206:209], v[182:185], 0
	v_mfma_f32_16x16x32_bf16 v[16:19], v[214:217], v[182:185], 0
	v_mfma_f32_16x16x32_bf16 v[12:15], v[206:209], v[190:193], 0
	v_mfma_f32_16x16x32_bf16 v[8:11], v[214:217], v[190:193], 0
	v_mfma_f32_16x16x32_bf16 v[4:7], v[206:209], v[198:201], 0
	v_mfma_f32_16x16x32_bf16 v[0:3], v[214:217], v[198:201], 0
	v_mfma_f32_16x16x32_bf16 v[28:31], v[210:213], v[178:181], v[28:31]
	v_mfma_f32_16x16x32_bf16 v[24:27], v[218:221], v[178:181], v[24:27]
	v_mfma_f32_16x16x32_bf16 v[20:23], v[210:213], v[186:189], v[20:23]
	v_mfma_f32_16x16x32_bf16 v[16:19], v[218:221], v[186:189], v[16:19]
	v_mfma_f32_16x16x32_bf16 v[12:15], v[210:213], v[194:197], v[12:15]
	v_mfma_f32_16x16x32_bf16 v[8:11], v[218:221], v[194:197], v[8:11]
	v_mfma_f32_16x16x32_bf16 v[4:7], v[210:213], v[202:205], v[4:7]
	v_mfma_f32_16x16x32_bf16 v[0:3], v[218:221], v[202:205], v[0:3]
	s_setprio 0
	s_barrier
	ds_read_b128 v[158:161], v145 offset:0
	ds_read_b128 v[162:165], v145 offset:1024
	ds_read_b128 v[166:169], v145 offset:2048
	ds_read_b128 v[170:173], v145 offset:3072
	s_add_u32 s38, s27, s14
	s_addc_u32 s39, s28, s15
	v_readfirstlane_b32 s45, v137
	s_mov_b32 m0, s45
	ds_read_b128 v[152:155], v144 offset:0
	ds_read_b128 v[178:181], v144 offset:1024
	ds_read_b128 v[182:185], v144 offset:2048
	ds_read_b128 v[186:189], v144 offset:3072
	ds_read_b128 v[190:193], v144 offset:4096
	ds_read_b128 v[194:197], v144 offset:5120
	ds_read_b128 v[198:201], v144 offset:6144
	ds_read_b128 v[202:205], v144 offset:7168
	s_nop 0
	global_load_lds_dwordx4 v130, s[38:39]
	s_add_u32 m0, m0, 0x2000
	s_nop 0
	global_load_lds_dwordx4 v128, s[38:39]
	ds_read_b128 v[206:209], v143 offset:0
	ds_read_b128 v[210:213], v143 offset:1024
	ds_read_b128 v[214:217], v143 offset:2048
	ds_read_b128 v[218:221], v143 offset:3072
	s_waitcnt vmcnt(8)
	s_waitcnt lgkmcnt(0)
	s_barrier
	s_waitcnt lgkmcnt(0)
	s_waitcnt lgkmcnt(0)
	s_setprio 1
	v_mfma_f32_16x16x32_bf16 v[124:127], v[158:161], v[152:155], v[124:127]
	v_mfma_f32_16x16x32_bf16 v[120:123], v[166:169], v[152:155], v[120:123]
	v_mfma_f32_16x16x32_bf16 v[116:119], v[158:161], v[182:185], v[116:119]
	v_mfma_f32_16x16x32_bf16 v[112:115], v[166:169], v[182:185], v[112:115]
	v_mfma_f32_16x16x32_bf16 v[108:111], v[158:161], v[190:193], v[108:111]
	v_mfma_f32_16x16x32_bf16 v[104:107], v[166:169], v[190:193], v[104:107]
	v_mfma_f32_16x16x32_bf16 v[100:103], v[158:161], v[198:201], v[100:103]
	v_mfma_f32_16x16x32_bf16 v[96:99], v[166:169], v[198:201], v[96:99]
	v_mfma_f32_16x16x32_bf16 v[124:127], v[162:165], v[178:181], v[124:127]
	v_mfma_f32_16x16x32_bf16 v[120:123], v[170:173], v[178:181], v[120:123]
	v_mfma_f32_16x16x32_bf16 v[116:119], v[162:165], v[186:189], v[116:119]
	v_mfma_f32_16x16x32_bf16 v[112:115], v[170:173], v[186:189], v[112:115]
	v_mfma_f32_16x16x32_bf16 v[108:111], v[162:165], v[194:197], v[108:111]
	v_mfma_f32_16x16x32_bf16 v[104:107], v[170:173], v[194:197], v[104:107]
	v_mfma_f32_16x16x32_bf16 v[100:103], v[162:165], v[202:205], v[100:103]
	v_mfma_f32_16x16x32_bf16 v[96:99], v[170:173], v[202:205], v[96:99]
	s_setprio 0
	s_waitcnt lgkmcnt(0)
	s_setprio 1
	v_mfma_f32_16x16x32_bf16 v[92:95], v[206:209], v[152:155], v[92:95]
	v_mfma_f32_16x16x32_bf16 v[88:91], v[214:217], v[152:155], v[88:91]
	v_mfma_f32_16x16x32_bf16 v[84:87], v[206:209], v[182:185], v[84:87]
	v_mfma_f32_16x16x32_bf16 v[80:83], v[214:217], v[182:185], v[80:83]
	v_mfma_f32_16x16x32_bf16 v[76:79], v[206:209], v[190:193], v[76:79]
	v_mfma_f32_16x16x32_bf16 v[72:75], v[214:217], v[190:193], v[72:75]
	v_mfma_f32_16x16x32_bf16 v[68:71], v[206:209], v[198:201], v[68:71]
	v_mfma_f32_16x16x32_bf16 v[64:67], v[214:217], v[198:201], v[64:67]
	v_mfma_f32_16x16x32_bf16 v[92:95], v[210:213], v[178:181], v[92:95]
	v_mfma_f32_16x16x32_bf16 v[88:91], v[218:221], v[178:181], v[88:91]
	v_mfma_f32_16x16x32_bf16 v[84:87], v[210:213], v[186:189], v[84:87]
	v_mfma_f32_16x16x32_bf16 v[80:83], v[218:221], v[186:189], v[80:83]
	v_mfma_f32_16x16x32_bf16 v[76:79], v[210:213], v[194:197], v[76:79]
	v_mfma_f32_16x16x32_bf16 v[72:75], v[218:221], v[194:197], v[72:75]
	v_mfma_f32_16x16x32_bf16 v[68:71], v[210:213], v[202:205], v[68:71]
	v_mfma_f32_16x16x32_bf16 v[64:67], v[218:221], v[202:205], v[64:67]
	s_setprio 0
	s_barrier
	s_add_u32 s38, s37, 0x180
	v_add_u32_e32 v150, 0x18000, v135
	s_addc_u32 s39, s40, 0
	v_readfirstlane_b32 s37, v150
	v_add_u32_e32 v151, 0x1a000, v135
	s_mov_b32 m0, s37
	global_load_lds_dwordx4 v176, s[38:39]
	s_add_u32 m0, m0, 0x2000
	s_nop 0
	global_load_lds_dwordx4 v132, s[38:39]
	s_add_u32 s38, s41, 0x180
	v_add_u32_e32 v152, 0x8000, v135
	s_addc_u32 s39, s42, 0
	v_readfirstlane_b32 s37, v152
	v_add_u32_e32 v153, 0xa000, v135
	s_mov_b32 m0, s37
	ds_read_b128 v[178:181], v142 offset:0
	ds_read_b128 v[182:185], v142 offset:1024
	ds_read_b128 v[186:189], v142 offset:2048
	ds_read_b128 v[190:193], v142 offset:3072
	ds_read_b128 v[194:197], v142 offset:4096
	ds_read_b128 v[198:201], v142 offset:5120
	ds_read_b128 v[202:205], v142 offset:6144
	ds_read_b128 v[222:225], v142 offset:7168
	global_load_lds_dwordx4 v130, s[38:39]
	s_add_u32 m0, m0, 0x2000
	s_nop 0
	global_load_lds_dwordx4 v128, s[38:39]
	s_add_u32 s38, s43, 0x180
	v_add_u32_e32 v154, 0x1c000, v135
	s_addc_u32 s39, s44, 0
	v_readfirstlane_b32 s37, v154
	v_add_u32_e32 v155, 0x1e000, v135
	s_mov_b32 m0, s37
	global_load_lds_dwordx4 v176, s[38:39]
	s_add_u32 m0, m0, 0x2000
	s_nop 0
	global_load_lds_dwordx4 v132, s[38:39]
	s_waitcnt vmcnt(8)
	s_waitcnt lgkmcnt(0)
	s_barrier
	s_waitcnt lgkmcnt(0)
	s_setprio 1
	v_mfma_f32_16x16x32_bf16 v[60:63], v[158:161], v[178:181], v[60:63]
	v_mfma_f32_16x16x32_bf16 v[56:59], v[166:169], v[178:181], v[56:59]
	v_mfma_f32_16x16x32_bf16 v[52:55], v[158:161], v[186:189], v[52:55]
	v_mfma_f32_16x16x32_bf16 v[48:51], v[166:169], v[186:189], v[48:51]
	v_mfma_f32_16x16x32_bf16 v[44:47], v[158:161], v[194:197], v[44:47]
	v_mfma_f32_16x16x32_bf16 v[40:43], v[166:169], v[194:197], v[40:43]
	v_mfma_f32_16x16x32_bf16 v[36:39], v[158:161], v[202:205], v[36:39]
	v_mfma_f32_16x16x32_bf16 v[32:35], v[166:169], v[202:205], v[32:35]
	v_mfma_f32_16x16x32_bf16 v[60:63], v[162:165], v[182:185], v[60:63]
	v_mfma_f32_16x16x32_bf16 v[56:59], v[170:173], v[182:185], v[56:59]
	v_mfma_f32_16x16x32_bf16 v[52:55], v[162:165], v[190:193], v[52:55]
	v_mfma_f32_16x16x32_bf16 v[48:51], v[170:173], v[190:193], v[48:51]
	v_mfma_f32_16x16x32_bf16 v[44:47], v[162:165], v[198:201], v[44:47]
	v_mfma_f32_16x16x32_bf16 v[40:43], v[170:173], v[198:201], v[40:43]
	v_mfma_f32_16x16x32_bf16 v[36:39], v[162:165], v[222:225], v[36:39]
	v_mfma_f32_16x16x32_bf16 v[32:35], v[170:173], v[222:225], v[32:35]
	s_setprio 0
	s_setprio 1
	v_mfma_f32_16x16x32_bf16 v[28:31], v[206:209], v[178:181], v[28:31]
	v_mfma_f32_16x16x32_bf16 v[24:27], v[214:217], v[178:181], v[24:27]
	v_mfma_f32_16x16x32_bf16 v[20:23], v[206:209], v[186:189], v[20:23]
	v_mfma_f32_16x16x32_bf16 v[16:19], v[214:217], v[186:189], v[16:19]
	v_mfma_f32_16x16x32_bf16 v[12:15], v[206:209], v[194:197], v[12:15]
	v_mfma_f32_16x16x32_bf16 v[8:11], v[214:217], v[194:197], v[8:11]
	v_mfma_f32_16x16x32_bf16 v[4:7], v[206:209], v[202:205], v[4:7]
	v_mfma_f32_16x16x32_bf16 v[0:3], v[214:217], v[202:205], v[0:3]
	v_mfma_f32_16x16x32_bf16 v[28:31], v[210:213], v[182:185], v[28:31]
	v_mfma_f32_16x16x32_bf16 v[24:27], v[218:221], v[182:185], v[24:27]
	v_mfma_f32_16x16x32_bf16 v[20:23], v[210:213], v[190:193], v[20:23]
	v_mfma_f32_16x16x32_bf16 v[16:19], v[218:221], v[190:193], v[16:19]
	v_mfma_f32_16x16x32_bf16 v[12:15], v[210:213], v[198:201], v[12:15]
	v_mfma_f32_16x16x32_bf16 v[8:11], v[218:221], v[198:201], v[8:11]
	v_mfma_f32_16x16x32_bf16 v[4:7], v[210:213], v[222:225], v[4:7]
	v_mfma_f32_16x16x32_bf16 v[0:3], v[218:221], v[222:225], v[0:3]
	s_setprio 0
	s_add_i32 s29, s29, 2
	s_add_u32 s14, s14, 0x100
	s_addc_u32 s15, s15, 0
	s_cmp_gt_u32 s29, 11
	s_barrier

.LBB0_104:
	v_and_b32_e32 v0, 15, v7
	v_and_b32_e32 v1, 48, v7
	v_lshlrev_b32_e32 v0, 6, v0
	v_lshlrev_b32_e32 v7, 2, v7
	v_or_b32_e32 v8, v0, v1
	v_and_b32_e32 v7, 32, v7
	s_lshl_b32 s1, s35, 13
	v_bitop3_b32 v144, v8, s1, v7 bitop3:0xde
	s_lshl_b32 s1, s11, 6
	v_bitop3_b32 v0, v0, v7, v1 bitop3:0x36
	s_and_b32 s1, s1, 0x3000
	v_or_b32_e32 v0, s1, v0
	s_add_u32 s1, s48, s26
	v_bfe_u32 v8, v134, 6, 2
	s_addc_u32 s26, s49, s27
	v_and_b32_e32 v1, 31, v5
	v_lshlrev_b32_e32 v7, 1, v5
	v_lshrrev_b32_e32 v6, 13, v6
	v_add_u32_e32 v5, v5, v8
	s_add_u32 s2, s52, s2
	v_and_b32_e32 v7, 24, v7
	v_and_b32_e32 v6, 4, v6
	v_sub_u32_e32 v1, v5, v1
	s_addc_u32 s3, s53, s3
	v_add3_u32 v1, v1, v7, v6
	v_lshl_or_b32 v136, v1, 11, v2
	v_and_b32_e32 v1, 31, v3
	v_lshlrev_b32_e32 v5, 1, v3
	v_lshrrev_b32_e32 v4, 13, v4
	v_add_u32_e32 v3, v3, v8
	s_add_u32 s20, s48, s20
	v_and_b32_e32 v5, 24, v5
	v_and_b32_e32 v4, 4, v4
	v_sub_u32_e32 v1, v3, v1
	s_addc_u32 s21, s49, s21
	v_add3_u32 v1, v1, v5, v4
	s_add_u32 s27, s52, s30
	v_or_b32_e32 v145, 0x10000, v0
	v_or_b32_e32 v143, 0x14000, v0
	v_lshl_or_b32 v137, v1, 11, v2
	s_addc_u32 s28, s53, s31
	v_or_b32_e32 v141, 0x18000, v0
	v_or_b32_e32 v139, 0x1c000, v0
	v_cndmask_b32_e64 v0, v128, v136, s[40:41]
	v_cndmask_b32_e64 v132, v176, v137, s[40:41]
	v_mov_b32_e32 v176, v0
	s_add_u32 s29, s1, 0x100
	v_add_u32_e32 v142, 0x4000, v144
	v_add_u32_e32 v140, 0x8000, v144
	v_add_u32_e32 v138, 0xc000, v144
	v_mov_b32_e32 v133, v177
	s_addc_u32 s30, s26, 0
	s_mov_b32 s31, -2
	s_mov_b64 s[40:41], 0
	s_nop 0
	ds_read_b128 v[148:151], v145 offset:0
	ds_read_b128 v[152:155], v145 offset:1024
	ds_read_b128 v[160:163], v145 offset:2048
	ds_read_b128 v[164:167], v145 offset:3072
	s_add_u32 s35, s1, s40
	s_addc_u32 s43, s26, s41
	s_add_u32 s42, s35, 0x80
	v_add_u32_e32 v158, 0xc000, v134
	s_addc_u32 s43, s43, 0
	v_readfirstlane_b32 s35, v158
	v_add_u32_e32 v159, 0xe000, v134
	s_mov_b32 m0, s35
	ds_read_b128 v[168:171], v144 offset:0
	ds_read_b128 v[172:175], v144 offset:1024
	ds_read_b128 v[178:181], v144 offset:2048
	ds_read_b128 v[182:185], v144 offset:3072
	ds_read_b128 v[186:189], v144 offset:4096
	ds_read_b128 v[190:193], v144 offset:5120
	ds_read_b128 v[194:197], v144 offset:6144
	ds_read_b128 v[198:201], v144 offset:7168
	global_load_lds_dwordx4 v128, s[42:43]
	s_add_u32 m0, m0, 0x2000
	s_nop 0
	global_load_lds_dwordx4 v130, s[42:43]
	ds_read_b128 v[202:205], v143 offset:0
	ds_read_b128 v[206:209], v143 offset:1024
	ds_read_b128 v[210:213], v143 offset:2048
	ds_read_b128 v[214:217], v143 offset:3072
	s_waitcnt vmcnt(8)
	s_waitcnt lgkmcnt(0)
	s_barrier
	s_waitcnt lgkmcnt(0)
	s_waitcnt lgkmcnt(0)
	s_setprio 1
	v_mfma_f32_16x16x32_bf16 v[124:127], v[148:151], v[168:171], 0
	v_mfma_f32_16x16x32_bf16 v[120:123], v[160:163], v[168:171], 0
	v_mfma_f32_16x16x32_bf16 v[116:119], v[148:151], v[178:181], 0
	v_mfma_f32_16x16x32_bf16 v[112:115], v[160:163], v[178:181], 0
	v_mfma_f32_16x16x32_bf16 v[108:111], v[148:151], v[186:189], 0
	v_mfma_f32_16x16x32_bf16 v[104:107], v[160:163], v[186:189], 0
	v_mfma_f32_16x16x32_bf16 v[100:103], v[148:151], v[194:197], 0
	v_mfma_f32_16x16x32_bf16 v[96:99], v[160:163], v[194:197], 0
	v_mfma_f32_16x16x32_bf16 v[124:127], v[152:155], v[172:175], v[124:127]
	v_mfma_f32_16x16x32_bf16 v[120:123], v[164:167], v[172:175], v[120:123]
	v_mfma_f32_16x16x32_bf16 v[116:119], v[152:155], v[182:185], v[116:119]
	v_mfma_f32_16x16x32_bf16 v[112:115], v[164:167], v[182:185], v[112:115]
	v_mfma_f32_16x16x32_bf16 v[108:111], v[152:155], v[190:193], v[108:111]
	v_mfma_f32_16x16x32_bf16 v[104:107], v[164:167], v[190:193], v[104:107]
	v_mfma_f32_16x16x32_bf16 v[100:103], v[152:155], v[198:201], v[100:103]
	v_mfma_f32_16x16x32_bf16 v[96:99], v[164:167], v[198:201], v[96:99]
	s_setprio 0
	s_waitcnt lgkmcnt(0)
	s_setprio 1
	v_mfma_f32_16x16x32_bf16 v[92:95], v[202:205], v[168:171], 0
	v_mfma_f32_16x16x32_bf16 v[88:91], v[210:213], v[168:171], 0
	v_mfma_f32_16x16x32_bf16 v[84:87], v[202:205], v[178:181], 0
	v_mfma_f32_16x16x32_bf16 v[80:83], v[210:213], v[178:181], 0
	v_mfma_f32_16x16x32_bf16 v[76:79], v[202:205], v[186:189], 0
	v_mfma_f32_16x16x32_bf16 v[72:75], v[210:213], v[186:189], 0
	v_mfma_f32_16x16x32_bf16 v[68:71], v[202:205], v[194:197], 0
	v_mfma_f32_16x16x32_bf16 v[64:67], v[210:213], v[194:197], 0
	v_mfma_f32_16x16x32_bf16 v[92:95], v[206:209], v[172:175], v[92:95]
	v_mfma_f32_16x16x32_bf16 v[88:91], v[214:217], v[172:175], v[88:91]
	v_mfma_f32_16x16x32_bf16 v[84:87], v[206:209], v[182:185], v[84:87]
	v_mfma_f32_16x16x32_bf16 v[80:83], v[214:217], v[182:185], v[80:83]
	v_mfma_f32_16x16x32_bf16 v[76:79], v[206:209], v[190:193], v[76:79]
	v_mfma_f32_16x16x32_bf16 v[72:75], v[214:217], v[190:193], v[72:75]
	v_mfma_f32_16x16x32_bf16 v[68:71], v[206:209], v[198:201], v[68:71]
	v_mfma_f32_16x16x32_bf16 v[64:67], v[214:217], v[198:201], v[64:67]
	s_setprio 0
	s_barrier
	s_add_u32 s35, s2, s40
	s_addc_u32 s45, s3, s41
	s_add_u32 s42, s35, 0x100
	v_add_u32_e32 v146, 0x10000, v134
	s_addc_u32 s43, s45, 0
	v_readfirstlane_b32 s51, v146
	s_mov_b32 m0, s51
	v_add_u32_e32 v147, 0x12000, v134
	global_load_lds_dwordx4 v176, s[42:43]
	s_add_u32 m0, m0, 0x2000
	s_nop 0
	global_load_lds_dwordx4 v132, s[42:43]
	s_add_u32 s51, s20, s40
	s_addc_u32 s54, s21, s41
	s_add_u32 s42, s51, 0x100
	s_addc_u32 s43, s54, 0
	v_readfirstlane_b32 s88, v134
	s_mov_b32 m0, s88
	ds_read_b128 v[168:171], v142 offset:0
	ds_read_b128 v[172:175], v142 offset:1024
	ds_read_b128 v[178:181], v142 offset:2048
	ds_read_b128 v[182:185], v142 offset:3072
	ds_read_b128 v[186:189], v142 offset:4096
	ds_read_b128 v[190:193], v142 offset:5120
	ds_read_b128 v[194:197], v142 offset:6144
	ds_read_b128 v[198:201], v142 offset:7168
	global_load_lds_dwordx4 v128, s[42:43]
	s_add_u32 m0, m0, 0x2000
	s_nop 0
	global_load_lds_dwordx4 v130, s[42:43]
	s_add_u32 s88, s27, s40
	s_addc_u32 s89, s28, s41
	s_add_u32 s42, s88, 0x100
	v_add_u32_e32 v226, 0x14000, v134
	s_addc_u32 s43, s89, 0
	v_readfirstlane_b32 s96, v226
	s_mov_b32 m0, s96
	v_add_u32_e32 v227, 0x16000, v134
	global_load_lds_dwordx4 v176, s[42:43]
	s_add_u32 m0, m0, 0x2000
	s_nop 0
	global_load_lds_dwordx4 v132, s[42:43]
	s_waitcnt vmcnt(8)
	s_waitcnt lgkmcnt(0)
	s_barrier
	s_waitcnt lgkmcnt(0)
	s_setprio 1
	v_mfma_f32_16x16x32_bf16 v[60:63], v[148:151], v[168:171], 0
	v_mfma_f32_16x16x32_bf16 v[56:59], v[160:163], v[168:171], 0
	v_mfma_f32_16x16x32_bf16 v[52:55], v[148:151], v[178:181], 0
	v_mfma_f32_16x16x32_bf16 v[48:51], v[160:163], v[178:181], 0
	v_mfma_f32_16x16x32_bf16 v[44:47], v[148:151], v[186:189], 0
	v_mfma_f32_16x16x32_bf16 v[40:43], v[160:163], v[186:189], 0
	v_mfma_f32_16x16x32_bf16 v[36:39], v[148:151], v[194:197], 0
	v_mfma_f32_16x16x32_bf16 v[32:35], v[160:163], v[194:197], 0
	v_mfma_f32_16x16x32_bf16 v[60:63], v[152:155], v[172:175], v[60:63]
	v_mfma_f32_16x16x32_bf16 v[56:59], v[164:167], v[172:175], v[56:59]
	v_mfma_f32_16x16x32_bf16 v[52:55], v[152:155], v[182:185], v[52:55]
	v_mfma_f32_16x16x32_bf16 v[48:51], v[164:167], v[182:185], v[48:51]
	v_mfma_f32_16x16x32_bf16 v[44:47], v[152:155], v[190:193], v[44:47]
	v_mfma_f32_16x16x32_bf16 v[40:43], v[164:167], v[190:193], v[40:43]
	v_mfma_f32_16x16x32_bf16 v[36:39], v[152:155], v[198:201], v[36:39]
	v_mfma_f32_16x16x32_bf16 v[32:35], v[164:167], v[198:201], v[32:35]
	s_setprio 0
	s_setprio 1
	v_mfma_f32_16x16x32_bf16 v[28:31], v[202:205], v[168:171], 0
	v_mfma_f32_16x16x32_bf16 v[24:27], v[210:213], v[168:171], 0
	v_mfma_f32_16x16x32_bf16 v[20:23], v[202:205], v[178:181], 0
	v_mfma_f32_16x16x32_bf16 v[16:19], v[210:213], v[178:181], 0
	v_mfma_f32_16x16x32_bf16 v[12:15], v[202:205], v[186:189], 0
	v_mfma_f32_16x16x32_bf16 v[8:11], v[210:213], v[186:189], 0
	v_mfma_f32_16x16x32_bf16 v[4:7], v[202:205], v[194:197], 0
	v_mfma_f32_16x16x32_bf16 v[0:3], v[210:213], v[194:197], 0
	v_mfma_f32_16x16x32_bf16 v[28:31], v[206:209], v[172:175], v[28:31]
	v_mfma_f32_16x16x32_bf16 v[24:27], v[214:217], v[172:175], v[24:27]
	v_mfma_f32_16x16x32_bf16 v[20:23], v[206:209], v[182:185], v[20:23]
	v_mfma_f32_16x16x32_bf16 v[16:19], v[214:217], v[182:185], v[16:19]
	v_mfma_f32_16x16x32_bf16 v[12:15], v[206:209], v[190:193], v[12:15]
	v_mfma_f32_16x16x32_bf16 v[8:11], v[214:217], v[190:193], v[8:11]
	v_mfma_f32_16x16x32_bf16 v[4:7], v[206:209], v[198:201], v[4:7]
	v_mfma_f32_16x16x32_bf16 v[0:3], v[214:217], v[198:201], v[0:3]
	s_setprio 0
	s_barrier
	ds_read_b128 v[160:163], v141 offset:0
	ds_read_b128 v[164:167], v141 offset:1024
	ds_read_b128 v[168:171], v141 offset:2048
	ds_read_b128 v[172:175], v141 offset:3072
	s_add_u32 s42, s29, s40
	v_add_u32_e32 v150, 0x4000, v134
	s_addc_u32 s43, s30, s41
	v_readfirstlane_b32 s96, v150
	s_mov_b32 m0, s96
	v_add_u32_e32 v151, 0x6000, v134
	ds_read_b128 v[154:157], v140 offset:0
	ds_read_b128 v[178:181], v140 offset:1024
	ds_read_b128 v[182:185], v140 offset:2048
	ds_read_b128 v[186:189], v140 offset:3072
	ds_read_b128 v[190:193], v140 offset:4096
	ds_read_b128 v[194:197], v140 offset:5120
	ds_read_b128 v[198:201], v140 offset:6144
	ds_read_b128 v[202:205], v140 offset:7168
	global_load_lds_dwordx4 v128, s[42:43]
	s_add_u32 m0, m0, 0x2000
	s_nop 0
	global_load_lds_dwordx4 v130, s[42:43]
	ds_read_b128 v[206:209], v139 offset:0
	ds_read_b128 v[210:213], v139 offset:1024
	ds_read_b128 v[214:217], v139 offset:2048
	ds_read_b128 v[218:221], v139 offset:3072
	s_waitcnt vmcnt(8)
	s_waitcnt lgkmcnt(0)
	s_barrier
	s_waitcnt lgkmcnt(0)
	s_waitcnt lgkmcnt(0)
	s_setprio 1
	v_mfma_f32_16x16x32_bf16 v[124:127], v[160:163], v[154:157], v[124:127]
	v_mfma_f32_16x16x32_bf16 v[120:123], v[168:171], v[154:157], v[120:123]
	v_mfma_f32_16x16x32_bf16 v[116:119], v[160:163], v[182:185], v[116:119]
	v_mfma_f32_16x16x32_bf16 v[112:115], v[168:171], v[182:185], v[112:115]
	v_mfma_f32_16x16x32_bf16 v[108:111], v[160:163], v[190:193], v[108:111]
	v_mfma_f32_16x16x32_bf16 v[104:107], v[168:171], v[190:193], v[104:107]
	v_mfma_f32_16x16x32_bf16 v[100:103], v[160:163], v[198:201], v[100:103]
	v_mfma_f32_16x16x32_bf16 v[96:99], v[168:171], v[198:201], v[96:99]
	v_mfma_f32_16x16x32_bf16 v[124:127], v[164:167], v[178:181], v[124:127]
	v_mfma_f32_16x16x32_bf16 v[120:123], v[172:175], v[178:181], v[120:123]
	v_mfma_f32_16x16x32_bf16 v[116:119], v[164:167], v[186:189], v[116:119]
	v_mfma_f32_16x16x32_bf16 v[112:115], v[172:175], v[186:189], v[112:115]
	v_mfma_f32_16x16x32_bf16 v[108:111], v[164:167], v[194:197], v[108:111]
	v_mfma_f32_16x16x32_bf16 v[104:107], v[172:175], v[194:197], v[104:107]
	v_mfma_f32_16x16x32_bf16 v[100:103], v[164:167], v[202:205], v[100:103]
	v_mfma_f32_16x16x32_bf16 v[96:99], v[172:175], v[202:205], v[96:99]
	s_setprio 0
	s_waitcnt lgkmcnt(0)
	s_setprio 1
	v_mfma_f32_16x16x32_bf16 v[92:95], v[206:209], v[154:157], v[92:95]
	v_mfma_f32_16x16x32_bf16 v[88:91], v[214:217], v[154:157], v[88:91]
	v_mfma_f32_16x16x32_bf16 v[84:87], v[206:209], v[182:185], v[84:87]
	v_mfma_f32_16x16x32_bf16 v[80:83], v[214:217], v[182:185], v[80:83]
	v_mfma_f32_16x16x32_bf16 v[76:79], v[206:209], v[190:193], v[76:79]
	v_mfma_f32_16x16x32_bf16 v[72:75], v[214:217], v[190:193], v[72:75]
	v_mfma_f32_16x16x32_bf16 v[68:71], v[206:209], v[198:201], v[68:71]
	v_mfma_f32_16x16x32_bf16 v[64:67], v[214:217], v[198:201], v[64:67]
	v_mfma_f32_16x16x32_bf16 v[92:95], v[210:213], v[178:181], v[92:95]
	v_mfma_f32_16x16x32_bf16 v[88:91], v[218:221], v[178:181], v[88:91]
	v_mfma_f32_16x16x32_bf16 v[84:87], v[210:213], v[186:189], v[84:87]
	v_mfma_f32_16x16x32_bf16 v[80:83], v[218:221], v[186:189], v[80:83]
	v_mfma_f32_16x16x32_bf16 v[76:79], v[210:213], v[194:197], v[76:79]
	v_mfma_f32_16x16x32_bf16 v[72:75], v[218:221], v[194:197], v[72:75]
	v_mfma_f32_16x16x32_bf16 v[68:71], v[210:213], v[202:205], v[68:71]
	v_mfma_f32_16x16x32_bf16 v[64:67], v[218:221], v[202:205], v[64:67]
	s_setprio 0
	s_barrier
	s_add_u32 s42, s35, 0x180
	v_add_u32_e32 v152, 0x18000, v134
	s_addc_u32 s43, s45, 0
	v_readfirstlane_b32 s35, v152
	v_add_u32_e32 v153, 0x1a000, v134
	s_mov_b32 m0, s35
	global_load_lds_dwordx4 v176, s[42:43]
	s_add_u32 m0, m0, 0x2000
	s_nop 0
	global_load_lds_dwordx4 v132, s[42:43]
	s_add_u32 s42, s51, 0x180
	v_add_u32_e32 v154, 0x8000, v134
	s_addc_u32 s43, s54, 0
	v_readfirstlane_b32 s35, v154
	v_add_u32_e32 v155, 0xa000, v134
	s_mov_b32 m0, s35
	ds_read_b128 v[178:181], v138 offset:0
	ds_read_b128 v[182:185], v138 offset:1024
	ds_read_b128 v[186:189], v138 offset:2048
	ds_read_b128 v[190:193], v138 offset:3072
	ds_read_b128 v[194:197], v138 offset:4096
	ds_read_b128 v[198:201], v138 offset:5120
	ds_read_b128 v[202:205], v138 offset:6144
	ds_read_b128 v[222:225], v138 offset:7168
	global_load_lds_dwordx4 v128, s[42:43]
	s_add_u32 m0, m0, 0x2000
	s_nop 0
	global_load_lds_dwordx4 v130, s[42:43]
	s_add_u32 s42, s88, 0x180
	v_add_u32_e32 v156, 0x1c000, v134
	s_addc_u32 s43, s89, 0
	v_readfirstlane_b32 s35, v156
	v_add_u32_e32 v157, 0x1e000, v134
	s_mov_b32 m0, s35
	global_load_lds_dwordx4 v176, s[42:43]
	s_add_u32 m0, m0, 0x2000
	s_nop 0
	global_load_lds_dwordx4 v132, s[42:43]
	s_waitcnt vmcnt(8)
	s_waitcnt lgkmcnt(0)
	s_barrier
	s_waitcnt lgkmcnt(0)
	s_setprio 1
	v_mfma_f32_16x16x32_bf16 v[60:63], v[160:163], v[178:181], v[60:63]
	v_mfma_f32_16x16x32_bf16 v[56:59], v[168:171], v[178:181], v[56:59]
	v_mfma_f32_16x16x32_bf16 v[52:55], v[160:163], v[186:189], v[52:55]
	v_mfma_f32_16x16x32_bf16 v[48:51], v[168:171], v[186:189], v[48:51]
	v_mfma_f32_16x16x32_bf16 v[44:47], v[160:163], v[194:197], v[44:47]
	v_mfma_f32_16x16x32_bf16 v[40:43], v[168:171], v[194:197], v[40:43]
	v_mfma_f32_16x16x32_bf16 v[36:39], v[160:163], v[202:205], v[36:39]
	v_mfma_f32_16x16x32_bf16 v[32:35], v[168:171], v[202:205], v[32:35]
	v_mfma_f32_16x16x32_bf16 v[60:63], v[164:167], v[182:185], v[60:63]
	v_mfma_f32_16x16x32_bf16 v[56:59], v[172:175], v[182:185], v[56:59]
	v_mfma_f32_16x16x32_bf16 v[52:55], v[164:167], v[190:193], v[52:55]
	v_mfma_f32_16x16x32_bf16 v[48:51], v[172:175], v[190:193], v[48:51]
	v_mfma_f32_16x16x32_bf16 v[44:47], v[164:167], v[198:201], v[44:47]
	v_mfma_f32_16x16x32_bf16 v[40:43], v[172:175], v[198:201], v[40:43]
	v_mfma_f32_16x16x32_bf16 v[36:39], v[164:167], v[222:225], v[36:39]
	v_mfma_f32_16x16x32_bf16 v[32:35], v[172:175], v[222:225], v[32:35]
	s_setprio 0
	s_setprio 1
	v_mfma_f32_16x16x32_bf16 v[28:31], v[206:209], v[178:181], v[28:31]
	v_mfma_f32_16x16x32_bf16 v[24:27], v[214:217], v[178:181], v[24:27]
	v_mfma_f32_16x16x32_bf16 v[20:23], v[206:209], v[186:189], v[20:23]
	v_mfma_f32_16x16x32_bf16 v[16:19], v[214:217], v[186:189], v[16:19]
	v_mfma_f32_16x16x32_bf16 v[12:15], v[206:209], v[194:197], v[12:15]
	v_mfma_f32_16x16x32_bf16 v[8:11], v[214:217], v[194:197], v[8:11]
	v_mfma_f32_16x16x32_bf16 v[4:7], v[206:209], v[202:205], v[4:7]
	v_mfma_f32_16x16x32_bf16 v[0:3], v[214:217], v[202:205], v[0:3]
	v_mfma_f32_16x16x32_bf16 v[28:31], v[210:213], v[182:185], v[28:31]
	v_mfma_f32_16x16x32_bf16 v[24:27], v[218:221], v[182:185], v[24:27]
	v_mfma_f32_16x16x32_bf16 v[20:23], v[210:213], v[190:193], v[20:23]
	v_mfma_f32_16x16x32_bf16 v[16:19], v[218:221], v[190:193], v[16:19]
	v_mfma_f32_16x16x32_bf16 v[12:15], v[210:213], v[198:201], v[12:15]
	v_mfma_f32_16x16x32_bf16 v[8:11], v[218:221], v[198:201], v[8:11]
	v_mfma_f32_16x16x32_bf16 v[4:7], v[210:213], v[222:225], v[4:7]
	v_mfma_f32_16x16x32_bf16 v[0:3], v[218:221], v[222:225], v[0:3]
	s_setprio 0
	s_add_i32 s31, s31, 2
	s_add_u32 s40, s40, 0x100
	s_addc_u32 s41, s41, 0
	s_cmp_gt_u32 s31, 11
	s_barrier

.LBB0_140:
	v_and_b32_e32 v0, 15, v7
	v_and_b32_e32 v1, 48, v7
	v_lshlrev_b32_e32 v0, 6, v0
	v_lshlrev_b32_e32 v7, 2, v7
	v_or_b32_e32 v8, v0, v1
	v_and_b32_e32 v7, 32, v7
	s_lshl_b32 s1, s35, 13
	v_bitop3_b32 v144, v8, s1, v7 bitop3:0xde
	s_lshl_b32 s1, s11, 6
	v_bitop3_b32 v0, v0, v7, v1 bitop3:0x36
	s_and_b32 s1, s1, 0x3000
	v_or_b32_e32 v0, s1, v0
	s_add_u32 s1, s48, s30
	v_bfe_u32 v8, v134, 6, 2
	s_addc_u32 s26, s49, s31
	v_and_b32_e32 v1, 31, v4
	v_lshlrev_b32_e32 v7, 1, v4
	v_lshrrev_b32_e32 v6, 13, v6
	v_add_u32_e32 v4, v4, v8
	s_add_u32 s27, s52, s42
	v_and_b32_e32 v7, 24, v7
	v_and_b32_e32 v6, 4, v6
	v_sub_u32_e32 v1, v4, v1
	s_addc_u32 s28, s53, s43
	v_add3_u32 v1, v1, v7, v6
	v_lshl_or_b32 v136, v1, 11, v2
	v_and_b32_e32 v1, 31, v3
	v_lshlrev_b32_e32 v4, 1, v3
	v_lshrrev_b32_e32 v5, 13, v5
	v_add_u32_e32 v3, v3, v8
	s_add_u32 s2, s48, s2
	v_and_b32_e32 v4, 24, v4
	v_and_b32_e32 v5, 4, v5
	v_sub_u32_e32 v1, v3, v1
	s_addc_u32 s3, s49, s3
	v_add3_u32 v1, v1, v4, v5
	s_add_u32 s20, s52, s20
	v_or_b32_e32 v145, 0x10000, v0
	v_or_b32_e32 v143, 0x14000, v0
	v_lshl_or_b32 v137, v1, 11, v2
	s_addc_u32 s21, s53, s21
	v_or_b32_e32 v141, 0x18000, v0
	v_or_b32_e32 v139, 0x1c000, v0
	v_cndmask_b32_e64 v0, v128, v136, s[40:41]
	v_cndmask_b32_e64 v132, v176, v137, s[40:41]
	v_mov_b32_e32 v176, v0
	s_add_u32 s29, s1, 0x100
	v_add_u32_e32 v142, 0x4000, v144
	v_add_u32_e32 v140, 0x8000, v144
	v_add_u32_e32 v138, 0xc000, v144
	v_mov_b32_e32 v133, v177
	s_addc_u32 s30, s26, 0
	s_mov_b32 s31, -2
	s_mov_b64 s[38:39], 0
	s_nop 0
	ds_read_b128 v[148:151], v145 offset:0
	ds_read_b128 v[152:155], v145 offset:1024
	ds_read_b128 v[160:163], v145 offset:2048
	ds_read_b128 v[164:167], v145 offset:3072
	s_add_u32 s35, s1, s38
	s_addc_u32 s41, s26, s39
	s_add_u32 s40, s35, 0x80
	v_add_u32_e32 v158, 0xc000, v134
	s_addc_u32 s41, s41, 0
	v_readfirstlane_b32 s35, v158
	v_add_u32_e32 v159, 0xe000, v134
	s_mov_b32 m0, s35
	ds_read_b128 v[168:171], v144 offset:0
	ds_read_b128 v[172:175], v144 offset:1024
	ds_read_b128 v[178:181], v144 offset:2048
	ds_read_b128 v[182:185], v144 offset:3072
	ds_read_b128 v[186:189], v144 offset:4096
	ds_read_b128 v[190:193], v144 offset:5120
	ds_read_b128 v[194:197], v144 offset:6144
	ds_read_b128 v[198:201], v144 offset:7168
	global_load_lds_dwordx4 v128, s[40:41]
	s_add_u32 m0, m0, 0x2000
	s_nop 0
	global_load_lds_dwordx4 v130, s[40:41]
	ds_read_b128 v[202:205], v143 offset:0
	ds_read_b128 v[206:209], v143 offset:1024
	ds_read_b128 v[210:213], v143 offset:2048
	ds_read_b128 v[214:217], v143 offset:3072
	s_waitcnt vmcnt(8)
	s_waitcnt lgkmcnt(0)
	s_barrier
	s_waitcnt lgkmcnt(0)
	s_waitcnt lgkmcnt(0)
	s_setprio 1
	v_mfma_f32_16x16x32_bf16 v[124:127], v[148:151], v[168:171], 0
	v_mfma_f32_16x16x32_bf16 v[120:123], v[160:163], v[168:171], 0
	v_mfma_f32_16x16x32_bf16 v[116:119], v[148:151], v[178:181], 0
	v_mfma_f32_16x16x32_bf16 v[112:115], v[160:163], v[178:181], 0
	v_mfma_f32_16x16x32_bf16 v[108:111], v[148:151], v[186:189], 0
	v_mfma_f32_16x16x32_bf16 v[104:107], v[160:163], v[186:189], 0
	v_mfma_f32_16x16x32_bf16 v[100:103], v[148:151], v[194:197], 0
	v_mfma_f32_16x16x32_bf16 v[96:99], v[160:163], v[194:197], 0
	v_mfma_f32_16x16x32_bf16 v[124:127], v[152:155], v[172:175], v[124:127]
	v_mfma_f32_16x16x32_bf16 v[120:123], v[164:167], v[172:175], v[120:123]
	v_mfma_f32_16x16x32_bf16 v[116:119], v[152:155], v[182:185], v[116:119]
	v_mfma_f32_16x16x32_bf16 v[112:115], v[164:167], v[182:185], v[112:115]
	v_mfma_f32_16x16x32_bf16 v[108:111], v[152:155], v[190:193], v[108:111]
	v_mfma_f32_16x16x32_bf16 v[104:107], v[164:167], v[190:193], v[104:107]
	v_mfma_f32_16x16x32_bf16 v[100:103], v[152:155], v[198:201], v[100:103]
	v_mfma_f32_16x16x32_bf16 v[96:99], v[164:167], v[198:201], v[96:99]
	s_setprio 0
	s_waitcnt lgkmcnt(0)
	s_setprio 1
	v_mfma_f32_16x16x32_bf16 v[92:95], v[202:205], v[168:171], 0
	v_mfma_f32_16x16x32_bf16 v[88:91], v[210:213], v[168:171], 0
	v_mfma_f32_16x16x32_bf16 v[84:87], v[202:205], v[178:181], 0
	v_mfma_f32_16x16x32_bf16 v[80:83], v[210:213], v[178:181], 0
	v_mfma_f32_16x16x32_bf16 v[76:79], v[202:205], v[186:189], 0
	v_mfma_f32_16x16x32_bf16 v[72:75], v[210:213], v[186:189], 0
	v_mfma_f32_16x16x32_bf16 v[68:71], v[202:205], v[194:197], 0
	v_mfma_f32_16x16x32_bf16 v[64:67], v[210:213], v[194:197], 0
	v_mfma_f32_16x16x32_bf16 v[92:95], v[206:209], v[172:175], v[92:95]
	v_mfma_f32_16x16x32_bf16 v[88:91], v[214:217], v[172:175], v[88:91]
	v_mfma_f32_16x16x32_bf16 v[84:87], v[206:209], v[182:185], v[84:87]
	v_mfma_f32_16x16x32_bf16 v[80:83], v[214:217], v[182:185], v[80:83]
	v_mfma_f32_16x16x32_bf16 v[76:79], v[206:209], v[190:193], v[76:79]
	v_mfma_f32_16x16x32_bf16 v[72:75], v[214:217], v[190:193], v[72:75]
	v_mfma_f32_16x16x32_bf16 v[68:71], v[206:209], v[198:201], v[68:71]
	v_mfma_f32_16x16x32_bf16 v[64:67], v[214:217], v[198:201], v[64:67]
	s_setprio 0
	s_barrier
	s_add_u32 s35, s27, s38
	s_addc_u32 s42, s28, s39
	s_add_u32 s40, s35, 0x100
	v_add_u32_e32 v146, 0x10000, v134
	s_addc_u32 s41, s42, 0
	v_readfirstlane_b32 s43, v146
	s_mov_b32 m0, s43
	v_add_u32_e32 v147, 0x12000, v134
	global_load_lds_dwordx4 v176, s[40:41]
	s_add_u32 m0, m0, 0x2000
	s_nop 0
	global_load_lds_dwordx4 v132, s[40:41]
	s_add_u32 s43, s2, s38
	s_addc_u32 s45, s3, s39
	s_add_u32 s40, s43, 0x100
	s_addc_u32 s41, s45, 0
	v_readfirstlane_b32 s48, v134
	s_mov_b32 m0, s48
	ds_read_b128 v[168:171], v142 offset:0
	ds_read_b128 v[172:175], v142 offset:1024
	ds_read_b128 v[178:181], v142 offset:2048
	ds_read_b128 v[182:185], v142 offset:3072
	ds_read_b128 v[186:189], v142 offset:4096
	ds_read_b128 v[190:193], v142 offset:5120
	ds_read_b128 v[194:197], v142 offset:6144
	ds_read_b128 v[198:201], v142 offset:7168
	global_load_lds_dwordx4 v128, s[40:41]
	s_add_u32 m0, m0, 0x2000
	s_nop 0
	global_load_lds_dwordx4 v130, s[40:41]
	s_add_u32 s48, s20, s38
	s_addc_u32 s49, s21, s39
	s_add_u32 s40, s48, 0x100
	v_add_u32_e32 v226, 0x14000, v134
	s_addc_u32 s41, s49, 0
	v_readfirstlane_b32 s51, v226
	s_mov_b32 m0, s51
	v_add_u32_e32 v227, 0x16000, v134
	global_load_lds_dwordx4 v176, s[40:41]
	s_add_u32 m0, m0, 0x2000
	s_nop 0
	global_load_lds_dwordx4 v132, s[40:41]
	s_waitcnt vmcnt(8)
	s_waitcnt lgkmcnt(0)
	s_barrier
	s_waitcnt lgkmcnt(0)
	s_setprio 1
	v_mfma_f32_16x16x32_bf16 v[60:63], v[148:151], v[168:171], 0
	v_mfma_f32_16x16x32_bf16 v[56:59], v[160:163], v[168:171], 0
	v_mfma_f32_16x16x32_bf16 v[52:55], v[148:151], v[178:181], 0
	v_mfma_f32_16x16x32_bf16 v[48:51], v[160:163], v[178:181], 0
	v_mfma_f32_16x16x32_bf16 v[44:47], v[148:151], v[186:189], 0
	v_mfma_f32_16x16x32_bf16 v[40:43], v[160:163], v[186:189], 0
	v_mfma_f32_16x16x32_bf16 v[36:39], v[148:151], v[194:197], 0
	v_mfma_f32_16x16x32_bf16 v[32:35], v[160:163], v[194:197], 0
	v_mfma_f32_16x16x32_bf16 v[60:63], v[152:155], v[172:175], v[60:63]
	v_mfma_f32_16x16x32_bf16 v[56:59], v[164:167], v[172:175], v[56:59]
	v_mfma_f32_16x16x32_bf16 v[52:55], v[152:155], v[182:185], v[52:55]
	v_mfma_f32_16x16x32_bf16 v[48:51], v[164:167], v[182:185], v[48:51]
	v_mfma_f32_16x16x32_bf16 v[44:47], v[152:155], v[190:193], v[44:47]
	v_mfma_f32_16x16x32_bf16 v[40:43], v[164:167], v[190:193], v[40:43]
	v_mfma_f32_16x16x32_bf16 v[36:39], v[152:155], v[198:201], v[36:39]
	v_mfma_f32_16x16x32_bf16 v[32:35], v[164:167], v[198:201], v[32:35]
	s_setprio 0
	s_setprio 1
	v_mfma_f32_16x16x32_bf16 v[28:31], v[202:205], v[168:171], 0
	v_mfma_f32_16x16x32_bf16 v[24:27], v[210:213], v[168:171], 0
	v_mfma_f32_16x16x32_bf16 v[20:23], v[202:205], v[178:181], 0
	v_mfma_f32_16x16x32_bf16 v[16:19], v[210:213], v[178:181], 0
	v_mfma_f32_16x16x32_bf16 v[12:15], v[202:205], v[186:189], 0
	v_mfma_f32_16x16x32_bf16 v[8:11], v[210:213], v[186:189], 0
	v_mfma_f32_16x16x32_bf16 v[4:7], v[202:205], v[194:197], 0
	v_mfma_f32_16x16x32_bf16 v[0:3], v[210:213], v[194:197], 0
	v_mfma_f32_16x16x32_bf16 v[28:31], v[206:209], v[172:175], v[28:31]
	v_mfma_f32_16x16x32_bf16 v[24:27], v[214:217], v[172:175], v[24:27]
	v_mfma_f32_16x16x32_bf16 v[20:23], v[206:209], v[182:185], v[20:23]
	v_mfma_f32_16x16x32_bf16 v[16:19], v[214:217], v[182:185], v[16:19]
	v_mfma_f32_16x16x32_bf16 v[12:15], v[206:209], v[190:193], v[12:15]
	v_mfma_f32_16x16x32_bf16 v[8:11], v[214:217], v[190:193], v[8:11]
	v_mfma_f32_16x16x32_bf16 v[4:7], v[206:209], v[198:201], v[4:7]
	v_mfma_f32_16x16x32_bf16 v[0:3], v[214:217], v[198:201], v[0:3]
	s_setprio 0
	s_barrier
	ds_read_b128 v[160:163], v141 offset:0
	ds_read_b128 v[164:167], v141 offset:1024
	ds_read_b128 v[168:171], v141 offset:2048
	ds_read_b128 v[172:175], v141 offset:3072
	s_add_u32 s40, s29, s38
	v_add_u32_e32 v150, 0x4000, v134
	s_addc_u32 s41, s30, s39
	v_readfirstlane_b32 s51, v150
	s_mov_b32 m0, s51
	v_add_u32_e32 v151, 0x6000, v134
	ds_read_b128 v[154:157], v140 offset:0
	ds_read_b128 v[178:181], v140 offset:1024
	ds_read_b128 v[182:185], v140 offset:2048
	ds_read_b128 v[186:189], v140 offset:3072
	ds_read_b128 v[190:193], v140 offset:4096
	ds_read_b128 v[194:197], v140 offset:5120
	ds_read_b128 v[198:201], v140 offset:6144
	ds_read_b128 v[202:205], v140 offset:7168
	global_load_lds_dwordx4 v128, s[40:41]
	s_add_u32 m0, m0, 0x2000
	s_nop 0
	global_load_lds_dwordx4 v130, s[40:41]
	ds_read_b128 v[206:209], v139 offset:0
	ds_read_b128 v[210:213], v139 offset:1024
	ds_read_b128 v[214:217], v139 offset:2048
	ds_read_b128 v[218:221], v139 offset:3072
	s_waitcnt vmcnt(8)
	s_waitcnt lgkmcnt(0)
	s_barrier
	s_waitcnt lgkmcnt(0)
	s_waitcnt lgkmcnt(0)
	s_setprio 1
	v_mfma_f32_16x16x32_bf16 v[124:127], v[160:163], v[154:157], v[124:127]
	v_mfma_f32_16x16x32_bf16 v[120:123], v[168:171], v[154:157], v[120:123]
	v_mfma_f32_16x16x32_bf16 v[116:119], v[160:163], v[182:185], v[116:119]
	v_mfma_f32_16x16x32_bf16 v[112:115], v[168:171], v[182:185], v[112:115]
	v_mfma_f32_16x16x32_bf16 v[108:111], v[160:163], v[190:193], v[108:111]
	v_mfma_f32_16x16x32_bf16 v[104:107], v[168:171], v[190:193], v[104:107]
	v_mfma_f32_16x16x32_bf16 v[100:103], v[160:163], v[198:201], v[100:103]
	v_mfma_f32_16x16x32_bf16 v[96:99], v[168:171], v[198:201], v[96:99]
	v_mfma_f32_16x16x32_bf16 v[124:127], v[164:167], v[178:181], v[124:127]
	v_mfma_f32_16x16x32_bf16 v[120:123], v[172:175], v[178:181], v[120:123]
	v_mfma_f32_16x16x32_bf16 v[116:119], v[164:167], v[186:189], v[116:119]
	v_mfma_f32_16x16x32_bf16 v[112:115], v[172:175], v[186:189], v[112:115]
	v_mfma_f32_16x16x32_bf16 v[108:111], v[164:167], v[194:197], v[108:111]
	v_mfma_f32_16x16x32_bf16 v[104:107], v[172:175], v[194:197], v[104:107]
	v_mfma_f32_16x16x32_bf16 v[100:103], v[164:167], v[202:205], v[100:103]
	v_mfma_f32_16x16x32_bf16 v[96:99], v[172:175], v[202:205], v[96:99]
	s_setprio 0
	s_waitcnt lgkmcnt(0)
	s_setprio 1
	v_mfma_f32_16x16x32_bf16 v[92:95], v[206:209], v[154:157], v[92:95]
	v_mfma_f32_16x16x32_bf16 v[88:91], v[214:217], v[154:157], v[88:91]
	v_mfma_f32_16x16x32_bf16 v[84:87], v[206:209], v[182:185], v[84:87]
	v_mfma_f32_16x16x32_bf16 v[80:83], v[214:217], v[182:185], v[80:83]
	v_mfma_f32_16x16x32_bf16 v[76:79], v[206:209], v[190:193], v[76:79]
	v_mfma_f32_16x16x32_bf16 v[72:75], v[214:217], v[190:193], v[72:75]
	v_mfma_f32_16x16x32_bf16 v[68:71], v[206:209], v[198:201], v[68:71]
	v_mfma_f32_16x16x32_bf16 v[64:67], v[214:217], v[198:201], v[64:67]
	v_mfma_f32_16x16x32_bf16 v[92:95], v[210:213], v[178:181], v[92:95]
	v_mfma_f32_16x16x32_bf16 v[88:91], v[218:221], v[178:181], v[88:91]
	v_mfma_f32_16x16x32_bf16 v[84:87], v[210:213], v[186:189], v[84:87]
	v_mfma_f32_16x16x32_bf16 v[80:83], v[218:221], v[186:189], v[80:83]
	v_mfma_f32_16x16x32_bf16 v[76:79], v[210:213], v[194:197], v[76:79]
	v_mfma_f32_16x16x32_bf16 v[72:75], v[218:221], v[194:197], v[72:75]
	v_mfma_f32_16x16x32_bf16 v[68:71], v[210:213], v[202:205], v[68:71]
	v_mfma_f32_16x16x32_bf16 v[64:67], v[218:221], v[202:205], v[64:67]
	s_setprio 0
	s_barrier
	s_add_u32 s40, s35, 0x180
	v_add_u32_e32 v152, 0x18000, v134
	s_addc_u32 s41, s42, 0
	v_readfirstlane_b32 s35, v152
	v_add_u32_e32 v153, 0x1a000, v134
	s_mov_b32 m0, s35
	global_load_lds_dwordx4 v176, s[40:41]
	s_add_u32 m0, m0, 0x2000
	s_nop 0
	global_load_lds_dwordx4 v132, s[40:41]
	s_add_u32 s40, s43, 0x180
	v_add_u32_e32 v154, 0x8000, v134
	s_addc_u32 s41, s45, 0
	v_readfirstlane_b32 s35, v154
	v_add_u32_e32 v155, 0xa000, v134
	s_mov_b32 m0, s35
	ds_read_b128 v[178:181], v138 offset:0
	ds_read_b128 v[182:185], v138 offset:1024
	ds_read_b128 v[186:189], v138 offset:2048
	ds_read_b128 v[190:193], v138 offset:3072
	ds_read_b128 v[194:197], v138 offset:4096
	ds_read_b128 v[198:201], v138 offset:5120
	ds_read_b128 v[202:205], v138 offset:6144
	ds_read_b128 v[222:225], v138 offset:7168
	global_load_lds_dwordx4 v128, s[40:41]
	s_add_u32 m0, m0, 0x2000
	s_nop 0
	global_load_lds_dwordx4 v130, s[40:41]
	s_add_u32 s40, s48, 0x180
	v_add_u32_e32 v156, 0x1c000, v134
	s_addc_u32 s41, s49, 0
	v_readfirstlane_b32 s35, v156
	v_add_u32_e32 v157, 0x1e000, v134
	s_mov_b32 m0, s35
	global_load_lds_dwordx4 v176, s[40:41]
	s_add_u32 m0, m0, 0x2000
	s_nop 0
	global_load_lds_dwordx4 v132, s[40:41]
	s_waitcnt vmcnt(8)
	s_waitcnt lgkmcnt(0)
	s_barrier
	s_waitcnt lgkmcnt(0)
	s_setprio 1
	v_mfma_f32_16x16x32_bf16 v[60:63], v[160:163], v[178:181], v[60:63]
	v_mfma_f32_16x16x32_bf16 v[56:59], v[168:171], v[178:181], v[56:59]
	v_mfma_f32_16x16x32_bf16 v[52:55], v[160:163], v[186:189], v[52:55]
	v_mfma_f32_16x16x32_bf16 v[48:51], v[168:171], v[186:189], v[48:51]
	v_mfma_f32_16x16x32_bf16 v[44:47], v[160:163], v[194:197], v[44:47]
	v_mfma_f32_16x16x32_bf16 v[40:43], v[168:171], v[194:197], v[40:43]
	v_mfma_f32_16x16x32_bf16 v[36:39], v[160:163], v[202:205], v[36:39]
	v_mfma_f32_16x16x32_bf16 v[32:35], v[168:171], v[202:205], v[32:35]
	v_mfma_f32_16x16x32_bf16 v[60:63], v[164:167], v[182:185], v[60:63]
	v_mfma_f32_16x16x32_bf16 v[56:59], v[172:175], v[182:185], v[56:59]
	v_mfma_f32_16x16x32_bf16 v[52:55], v[164:167], v[190:193], v[52:55]
	v_mfma_f32_16x16x32_bf16 v[48:51], v[172:175], v[190:193], v[48:51]
	v_mfma_f32_16x16x32_bf16 v[44:47], v[164:167], v[198:201], v[44:47]
	v_mfma_f32_16x16x32_bf16 v[40:43], v[172:175], v[198:201], v[40:43]
	v_mfma_f32_16x16x32_bf16 v[36:39], v[164:167], v[222:225], v[36:39]
	v_mfma_f32_16x16x32_bf16 v[32:35], v[172:175], v[222:225], v[32:35]
	s_setprio 0
	s_setprio 1
	v_mfma_f32_16x16x32_bf16 v[28:31], v[206:209], v[178:181], v[28:31]
	v_mfma_f32_16x16x32_bf16 v[24:27], v[214:217], v[178:181], v[24:27]
	v_mfma_f32_16x16x32_bf16 v[20:23], v[206:209], v[186:189], v[20:23]
	v_mfma_f32_16x16x32_bf16 v[16:19], v[214:217], v[186:189], v[16:19]
	v_mfma_f32_16x16x32_bf16 v[12:15], v[206:209], v[194:197], v[12:15]
	v_mfma_f32_16x16x32_bf16 v[8:11], v[214:217], v[194:197], v[8:11]
	v_mfma_f32_16x16x32_bf16 v[4:7], v[206:209], v[202:205], v[4:7]
	v_mfma_f32_16x16x32_bf16 v[0:3], v[214:217], v[202:205], v[0:3]
	v_mfma_f32_16x16x32_bf16 v[28:31], v[210:213], v[182:185], v[28:31]
	v_mfma_f32_16x16x32_bf16 v[24:27], v[218:221], v[182:185], v[24:27]
	v_mfma_f32_16x16x32_bf16 v[20:23], v[210:213], v[190:193], v[20:23]
	v_mfma_f32_16x16x32_bf16 v[16:19], v[218:221], v[190:193], v[16:19]
	v_mfma_f32_16x16x32_bf16 v[12:15], v[210:213], v[198:201], v[12:15]
	v_mfma_f32_16x16x32_bf16 v[8:11], v[218:221], v[198:201], v[8:11]
	v_mfma_f32_16x16x32_bf16 v[4:7], v[210:213], v[222:225], v[4:7]
	v_mfma_f32_16x16x32_bf16 v[0:3], v[218:221], v[222:225], v[0:3]
	s_setprio 0
	s_add_i32 s31, s31, 2
	s_add_u32 s38, s38, 0x100
	s_addc_u32 s39, s39, 0
	s_cmp_gt_u32 s31, 11
	s_barrier
